# c41 + gemm1 K-loop: one static s_setprio 1 for waves 4-7 before the loop, the per-MFMA-group priority flips deleted, priority reset after the last group
# baseline (speedup 1.0000x reference)
; #define LDSAS __attribute__((address_space(3)))
; #define G_ISSUE(kt, st) do { G_ISSUE1(kt, st, 0); G_ISSUE1(kt, st, 1); G_ISSUE1(kt, st, 2); G_ISSUE1(kt, st, 3); } while (0)
; template <bool LOWREG = false>
; __device__ __forceinline__ void gemm_core(const bf16_t* __restrict__ A, int lda, const bf16_t* __restrict__ Bt, int ldb, int K, f32x4 (&acc)[8][4], unsigned char* smem, int tid) {
;     asm volatile("" : "+v"(tid));
;     const int lane = tid & 63, w = __builtin_amdgcn_readfirstlane(tid >> 6), wm = w >> 2, wn = w & 3, idx = lane & 15, kq = lane >> 4;
;     unsigned offA[4], offB[4];
; #pragma unroll
;     for (int j = 0; j < 4; ++j) { const int row = (j * 8 + w) * 8 + (lane >> 3), c = (lane & 7) ^ ((row >> 1) & 7);
;         offA[j] = (unsigned)(row * lda + c * 8) * 2u; offB[j] = (unsigned)(row * ldb + c * 8) * 2u; }
; #pragma unroll
;     for (int mi = 0; mi < 8; ++mi)
; #pragma unroll
;         for (int ni = 0; ni < 4; ++ni) acc[mi][ni] = (f32x4){0.f, 0.f, 0.f, 0.f};
;     LDSAS unsigned char* lds = (LDSAS unsigned char*)smem;
;     ...
;     const int nk = K >> 6;
;     G_ISSUE(0, 0);
;     asm volatile("s_waitcnt vmcnt(0)" ::: "memory");
;     __syncthreads();
;     const int swz = (idx >> 1) & 7;
;     const int aoff = (wm * 128 + idx) * 128, boff = G_AB + (wn * 64 + idx) * 128;
; __device__ void gemm1_phase(const Params& p, int l, int hb, unsigned char* smem) {
;     ...
;     for (int t = blockIdx.x; t < NTILES; t += gridDim.x) {
;         const int grp = t / GRP, r = t % GRP, jx = NT * (r & 7) + (r >> 3), mt = grp * 8 + (jx & 7), nt = jx >> 3;
;         const int m0 = mt * 256, n0 = nt * 256;
;         f32x4 acc[8][4];
;         int tid = threadIdx.x;
;         gemm_core(H + (size_t)m0 * 1024, 1024, Wt + (size_t)n0 * 1024, 1024, 1024, acc, smem, tid);
.Lg1_nosplit:
	s_mul_hi_i32 s9, s99, 0x78787879
	s_lshr_b32 s11, s9, 31
	s_ashr_i32 s9, s9, 7
	s_add_i32 s9, s9, s11
	s_mul_i32 s11, s9, 0x110
	s_sub_i32 s11, s99, s11
	s_and_b32 s12, s11, 7
	s_mul_i32 s12, s12, 34
	s_ashr_i32 s11, s11, 3
	s_add_i32 s12, s12, s11
	s_lshl_b32 s11, s12, 8
	s_lshl_b32 s9, s9, 11
	s_and_b32 s11, s11, 0x700
	s_or_b32 s56, s11, s9
	s_lshr_b32 s36, s12, 3
	s_lshr_b32 s11, s9, 11
	s_mul_i32 s11, s11, 5
	s_add_i32 s36, s36, s11
	s_mul_i32 s11, s36, 1928
	s_lshr_b32 s11, s11, 16
	s_mul_i32 s11, s11, 34
	s_sub_i32 s36, s36, s11
	s_lshl_b32 s36, s36, 8
	s_mov_b32 s11, s36
	s_ashr_i32 s57, s56, 31
	s_lshl_b64 s[16:17], s[56:57], 11
	s_add_u32 s18, s92, s16
	s_addc_u32 s19, s93, s17
	s_ashr_i32 s37, s36, 31
	s_lshl_b64 s[20:21], s[36:37], 11
	v_mov_b32_e32 v0, v210
	s_add_u32 s22, s94, s20
	s_addc_u32 s23, s95, s21
	v_readfirstlane_b32 s12, v0
	s_ashr_i32 s24, s12, 6
	s_and_b32 s101, s24, 3
	s_cmp_lg_u32 s101, 0
	s_cselect_b32 s101, 1, 2
	s_cmp_eq_u32 s36, 0x2100
	s_cselect_b32 s101, s101, 0
	s_lshr_b32 s98, s24, 2
	s_cmp_lg_u32 s98, s100
	s_cselect_b32 s98, 1, 0
	s_cmp_lt_i32 s100, 0
	s_cselect_b32 s98, 0, s98
	s_or_b32 s101, s101, s98
	v_bfe_u32 v2, v0, 3, 3
	v_lshl_or_b32 v3, s24, 3, v2
	v_lshrrev_b32_e32 v4, 1, v3
	v_xor_b32_e32 v4, v4, v0
	v_lshlrev_b32_e32 v4, 4, v4
	s_lshl_b32 s9, s24, 10
	v_and_b32_e32 v4, 0x70, v4
	s_add_i32 s9, s9, 0
	v_lshl_or_b32 v3, v3, 11, v4
	s_mov_b32 m0, s9
	v_add_u32_e32 v5, 0x20000, v3
	global_load_lds_dwordx4 v3, s[18:19]
	s_add_i32 m0, s9, 0x8000
	v_add_u32_e32 v6, 0x40000, v3
	global_load_lds_dwordx4 v3, s[22:23]
	s_add_i32 m0, s9, 0x2000
	v_add_u32_e32 v7, 0x60000, v3
	global_load_lds_dwordx4 v5, s[18:19]
	s_add_i32 m0, s9, 0xa000
	v_and_b32_e32 v1, 15, v0
	global_load_lds_dwordx4 v5, s[22:23]
	s_add_i32 m0, s9, 0x4000
	v_bfe_u32 v8, v0, 4, 2
	global_load_lds_dwordx4 v6, s[18:19]
	s_add_i32 m0, s9, 0xc000
	v_lshrrev_b32_e32 v3, 1, v0
	global_load_lds_dwordx4 v6, s[22:23]
	s_add_i32 m0, s9, 0x6000
	v_bfe_u32 v0, v0, 1, 3
	global_load_lds_dwordx4 v7, s[18:19]
	s_add_i32 m0, s9, 0xe000
	s_lshr_b32 s18, s12, 1
	global_load_lds_dwordx4 v7, s[22:23]
	s_and_b32 s18, s18, 0x1ffff80
	s_and_b32 s12, s12, 0xc0
	v_or_b32_e32 v5, s18, v1
	v_or_b32_e32 v1, s12, v1
	s_lshl_b32 s12, s24, 14
	s_add_u32 s16, s96, s16
	v_lshlrev_b32_e32 v149, 7, v5
	v_bitop3_b32 v0, v8, v0, 4 bitop3:0x36
	v_lshlrev_b32_e32 v5, 11, v2
	s_addc_u32 s17, s97, s17
	s_add_i32 s18, s12, 0x20000
	v_lshlrev_b32_e32 v147, 7, v1
	v_bitop3_b32 v1, v8, v3, 7 bitop3:0x78
	v_lshlrev_b32_e32 v146, 4, v0
	v_or3_b32 v80, s12, v5, v4
	v_or3_b32 v0, s18, v5, v4
	s_add_i32 s18, s12, 0x40000
	s_add_i32 s12, s12, 0x60000
	v_lshlrev_b32_e32 v148, 4, v1
	v_mov_b32_e32 v1, v81
	v_or3_b32 v2, s18, v5, v4
	v_mov_b32_e32 v3, v81
	v_or3_b32 v4, s12, v5, v4
	v_mov_b32_e32 v5, v81
	v_lshl_add_u64 v[130:131], s[16:17], 0, v[80:81]
	v_lshl_add_u64 v[132:133], s[16:17], 0, v[0:1]
	v_lshl_add_u64 v[134:135], s[16:17], 0, v[2:3]
	v_lshl_add_u64 v[136:137], s[16:17], 0, v[4:5]
	s_add_u32 s16, s64, s20
	s_waitcnt vmcnt(0)
	s_addc_u32 s17, s65, s21
	v_lshl_add_u64 v[140:141], s[16:17], 0, v[0:1]
	v_mov_b32_e32 v0, 0
	v_lshl_add_u64 v[138:139], s[16:17], 0, v[80:81]
	v_lshl_add_u64 v[142:143], s[16:17], 0, v[2:3]
	v_lshl_add_u64 v[144:145], s[16:17], 0, v[4:5]
	s_mov_b32 s12, 0
	s_mov_b64 s[38:39], 0
	v_mov_b32_e32 v1, v0
	v_mov_b32_e32 v2, v0
	v_mov_b32_e32 v3, v0
	v_mov_b32_e32 v4, v0
	v_mov_b32_e32 v5, v0
	v_mov_b32_e32 v6, v0
	v_mov_b32_e32 v7, v0
	v_mov_b32_e32 v8, v0
	v_mov_b32_e32 v9, v0
	s_waitcnt vmcnt(0)
	v_mov_b32_e32 v10, v0
	v_mov_b32_e32 v11, v0
	v_mov_b32_e32 v12, v0
	v_mov_b32_e32 v13, v0
	v_mov_b32_e32 v14, v0
	v_mov_b32_e32 v15, v0
	v_mov_b32_e32 v16, v0
	v_mov_b32_e32 v17, v0
	v_mov_b32_e32 v18, v0
	v_mov_b32_e32 v19, v0
	v_mov_b32_e32 v20, v0
	v_mov_b32_e32 v21, v0
	v_mov_b32_e32 v22, v0
	v_mov_b32_e32 v23, v0
	v_mov_b32_e32 v24, v0
	v_mov_b32_e32 v25, v0
	v_mov_b32_e32 v26, v0
	v_mov_b32_e32 v27, v0
	v_mov_b32_e32 v28, v0
	v_mov_b32_e32 v29, v0
	v_mov_b32_e32 v30, v0
	v_mov_b32_e32 v31, v0
	v_mov_b32_e32 v32, v0
	v_mov_b32_e32 v33, v0
	v_mov_b32_e32 v34, v0
	v_mov_b32_e32 v35, v0
	v_mov_b32_e32 v36, v0
	v_mov_b32_e32 v37, v0
	v_mov_b32_e32 v38, v0
	v_mov_b32_e32 v39, v0
	v_mov_b32_e32 v40, v0
	v_mov_b32_e32 v41, v0
	v_mov_b32_e32 v42, v0
	v_mov_b32_e32 v43, v0
	v_mov_b32_e32 v44, v0
	v_mov_b32_e32 v45, v0
	v_mov_b32_e32 v46, v0
	v_mov_b32_e32 v47, v0
	v_mov_b32_e32 v48, v0
	v_mov_b32_e32 v49, v0
	v_mov_b32_e32 v50, v0
	v_mov_b32_e32 v51, v0
	v_mov_b32_e32 v52, v0
	v_mov_b32_e32 v53, v0
	v_mov_b32_e32 v54, v0
	v_mov_b32_e32 v55, v0
	v_mov_b32_e32 v56, v0
	v_mov_b32_e32 v57, v0
	v_mov_b32_e32 v58, v0
	v_mov_b32_e32 v59, v0
	v_mov_b32_e32 v60, v0
	v_mov_b32_e32 v61, v0
	v_mov_b32_e32 v62, v0
	v_mov_b32_e32 v63, v0
	v_mov_b32_e32 v64, v0
	v_mov_b32_e32 v65, v0
	v_mov_b32_e32 v66, v0
	v_mov_b32_e32 v67, v0
	v_mov_b32_e32 v68, v0
	v_mov_b32_e32 v69, v0
	v_mov_b32_e32 v70, v0
	v_mov_b32_e32 v71, v0
	v_mov_b32_e32 v72, v0
	v_mov_b32_e32 v73, v0
	v_mov_b32_e32 v74, v0
	v_mov_b32_e32 v75, v0
	v_mov_b32_e32 v76, v0
	v_mov_b32_e32 v77, v0
	v_mov_b32_e32 v78, v0
	v_mov_b32_e32 v79, v0
	v_mov_b32_e32 v82, v0
	v_mov_b32_e32 v83, v0
	v_mov_b32_e32 v84, v0
	v_mov_b32_e32 v85, v0
	v_mov_b32_e32 v86, v0
	v_mov_b32_e32 v87, v0
	v_mov_b32_e32 v88, v0
	v_mov_b32_e32 v89, v0
	v_mov_b32_e32 v90, v0
	v_mov_b32_e32 v91, v0
	v_mov_b32_e32 v92, v0
	v_mov_b32_e32 v93, v0
	v_mov_b32_e32 v94, v0
	v_mov_b32_e32 v95, v0
	v_mov_b32_e32 v96, v0
	v_mov_b32_e32 v97, v0
	v_mov_b32_e32 v98, v0
	v_mov_b32_e32 v99, v0
	v_mov_b32_e32 v100, v0
	v_mov_b32_e32 v101, v0
	v_mov_b32_e32 v102, v0
	v_mov_b32_e32 v103, v0
	v_mov_b32_e32 v104, v0
	v_mov_b32_e32 v105, v0
	v_mov_b32_e32 v106, v0
	v_mov_b32_e32 v107, v0
	v_mov_b32_e32 v108, v0
	v_mov_b32_e32 v109, v0
	v_mov_b32_e32 v110, v0
	v_mov_b32_e32 v111, v0
	v_mov_b32_e32 v112, v0
	v_mov_b32_e32 v113, v0
	v_mov_b32_e32 v114, v0
	v_mov_b32_e32 v115, v0
	v_mov_b32_e32 v116, v0
	v_mov_b32_e32 v117, v0
	v_mov_b32_e32 v118, v0
	v_mov_b32_e32 v119, v0
	v_mov_b32_e32 v120, v0
	v_mov_b32_e32 v121, v0
	v_mov_b32_e32 v122, v0
	v_mov_b32_e32 v123, v0
	v_mov_b32_e32 v124, v0
	v_mov_b32_e32 v125, v0
	v_mov_b32_e32 v126, v0
	v_mov_b32_e32 v127, v0
	v_mov_b32_e32 v128, v0
	v_mov_b32_e32 v129, v0
	s_waitcnt lgkmcnt(0)
	s_barrier
	s_cmp_ge_u32 s24, 4
	s_cbranch_scc0 .Lg1_prio_done
	s_setprio 1
; template <bool LOWREG = false>
; __device__ __forceinline__ void gemm_core(const bf16_t* __restrict__ A, int lda, const bf16_t* __restrict__ Bt, int ldb, int K, f32x4 (&acc)[8][4], unsigned char* smem, int tid) {
;     ...
;     for (int kt = 0; kt < nk; ++kt) {
;         const int st = kt & 1;
;         const bool more = kt + 1 < nk;
;         const unsigned char* sb = smem + st * G_STAGE;
;         if constexpr (!LOWREG) {
; #pragma unroll
;         for (int ks = 0; ks < 2; ++ks) {
;             bf16x8 bfr[4], af[8];
;             const int co = ((ks * 4 + kq) ^ swz) * 16;
; #pragma unroll
;             for (int ni = 0; ni < 4; ++ni) bfr[ni] = *(const bf16x8*)(sb + boff + ni * 2048 + co);
; #pragma unroll
;             for (int mi = 0; mi < 8; ++mi) af[mi] = *(const bf16x8*)(sb + aoff + mi * 2048 + co);
;             if (more) { G_ISSUE1(kt + 1, st ^ 1, ks * 2); G_ISSUE1(kt + 1, st ^ 1, ks * 2 + 1); }
;             __builtin_amdgcn_sched_barrier(0);
;             __builtin_amdgcn_s_setprio(1);
; #pragma unroll
;             for (int mi = 0; mi < 8; ++mi)
; #pragma unroll
;                 for (int ni = 0; ni < 4; ++ni) acc[mi][ni] = __builtin_amdgcn_mfma_f32_16x16x32_bf16(bfr[ni], af[mi], acc[mi][ni], 0, 0, 0);
;             __builtin_amdgcn_s_setprio(0);
;             __builtin_amdgcn_sched_barrier(0);
;         }
.Lg1_prio_done:
.LBB0_255:
	s_and_b32 s16, s12, 0x10000
	s_add_i32 s17, s16, 0
	s_xor_b32 s16, s16, 0x10000
	v_add_u32_e32 v80, s17, v147
	v_add_u32_e32 v179, s17, v149
	s_add_i32 s16, s9, s16
	v_add_u32_e32 v162, v80, v148
	v_add_u32_e32 v196, v179, v148
	v_lshl_add_u64 v[200:201], v[130:131], 0, s[38:39]
	s_mov_b32 m0, s16
	ds_read_b128 v[150:153], v162 offset:32768
	ds_read_b128 v[154:157], v162 offset:34816
	ds_read_b128 v[158:161], v162 offset:36864
	ds_read_b128 v[162:165], v162 offset:38912
	ds_read_b128 v[166:169], v196
	ds_read_b128 v[170:173], v196 offset:2048
	ds_read_b128 v[174:177], v196 offset:4096
	ds_read_b128 v[180:183], v196 offset:6144
	ds_read_b128 v[184:187], v196 offset:8192
	ds_read_b128 v[188:191], v196 offset:10240
	ds_read_b128 v[192:195], v196 offset:12288
	ds_read_b128 v[196:199], v196 offset:14336
	global_load_lds_dwordx4 v[200:201], off
	v_lshl_add_u64 v[200:201], v[138:139], 0, s[38:39]
	s_add_i32 m0, s16, 0x8000
	s_nop 0
	global_load_lds_dwordx4 v[200:201], off
	v_lshl_add_u64 v[200:201], v[132:133], 0, s[38:39]
	s_add_i32 m0, s16, 0x2000
	s_nop 0
	global_load_lds_dwordx4 v[200:201], off
	v_lshl_add_u64 v[200:201], v[140:141], 0, s[38:39]
	s_add_i32 m0, s16, 0xa000
	s_nop 0
	global_load_lds_dwordx4 v[200:201], off
	s_cmp_lg_u32 s101, 0
	s_cbranch_scc1 .Lg1_dtalt1
	s_waitcnt lgkmcnt(0)
	v_mfma_f32_16x16x32_bf16 v[126:129], v[150:153], v[166:169], v[126:129]
	v_mfma_f32_16x16x32_bf16 v[122:125], v[154:157], v[166:169], v[122:125]
	v_mfma_f32_16x16x32_bf16 v[118:121], v[158:161], v[166:169], v[118:121]
	v_mfma_f32_16x16x32_bf16 v[114:117], v[162:165], v[166:169], v[114:117]
	v_mfma_f32_16x16x32_bf16 v[110:113], v[150:153], v[170:173], v[110:113]
	v_mfma_f32_16x16x32_bf16 v[106:109], v[154:157], v[170:173], v[106:109]
	v_mfma_f32_16x16x32_bf16 v[102:105], v[158:161], v[170:173], v[102:105]
	v_mfma_f32_16x16x32_bf16 v[98:101], v[162:165], v[170:173], v[98:101]
	v_mfma_f32_16x16x32_bf16 v[94:97], v[150:153], v[174:177], v[94:97]
	v_mfma_f32_16x16x32_bf16 v[90:93], v[154:157], v[174:177], v[90:93]
	v_mfma_f32_16x16x32_bf16 v[86:89], v[158:161], v[174:177], v[86:89]
	v_mfma_f32_16x16x32_bf16 v[82:85], v[162:165], v[174:177], v[82:85]
	v_mfma_f32_16x16x32_bf16 v[76:79], v[150:153], v[180:183], v[76:79]
	v_mfma_f32_16x16x32_bf16 v[72:75], v[154:157], v[180:183], v[72:75]
	v_mfma_f32_16x16x32_bf16 v[68:71], v[158:161], v[180:183], v[68:71]
	v_mfma_f32_16x16x32_bf16 v[64:67], v[162:165], v[180:183], v[64:67]
	v_mfma_f32_16x16x32_bf16 v[60:63], v[150:153], v[184:187], v[60:63]
	v_mfma_f32_16x16x32_bf16 v[56:59], v[154:157], v[184:187], v[56:59]
	v_mfma_f32_16x16x32_bf16 v[52:55], v[158:161], v[184:187], v[52:55]
	v_mfma_f32_16x16x32_bf16 v[48:51], v[162:165], v[184:187], v[48:51]
	v_mfma_f32_16x16x32_bf16 v[44:47], v[150:153], v[188:191], v[44:47]
	v_mfma_f32_16x16x32_bf16 v[40:43], v[154:157], v[188:191], v[40:43]
	v_mfma_f32_16x16x32_bf16 v[36:39], v[158:161], v[188:191], v[36:39]
	v_mfma_f32_16x16x32_bf16 v[32:35], v[162:165], v[188:191], v[32:35]
	v_mfma_f32_16x16x32_bf16 v[28:31], v[150:153], v[192:195], v[28:31]
	v_mfma_f32_16x16x32_bf16 v[24:27], v[154:157], v[192:195], v[24:27]
	v_mfma_f32_16x16x32_bf16 v[20:23], v[158:161], v[192:195], v[20:23]
	v_mfma_f32_16x16x32_bf16 v[16:19], v[162:165], v[192:195], v[16:19]
	v_mfma_f32_16x16x32_bf16 v[12:15], v[150:153], v[196:199], v[12:15]
	v_mfma_f32_16x16x32_bf16 v[8:11], v[154:157], v[196:199], v[8:11]
	v_mfma_f32_16x16x32_bf16 v[4:7], v[158:161], v[196:199], v[4:7]
	v_mfma_f32_16x16x32_bf16 v[0:3], v[162:165], v[196:199], v[0:3]
.Lg1_dtskip1:
	s_waitcnt lgkmcnt(0)
	v_add_u32_e32 v80, v80, v146
	ds_read_b128 v[150:153], v80 offset:32768
	ds_read_b128 v[154:157], v80 offset:34816
	ds_read_b128 v[158:161], v80 offset:36864
	ds_read_b128 v[162:165], v80 offset:38912
	v_add_u32_e32 v80, v179, v146
	v_lshl_add_u64 v[200:201], v[134:135], 0, s[38:39]
	s_add_i32 m0, s16, 0x4000
	ds_read_b128 v[166:169], v80
	ds_read_b128 v[170:173], v80 offset:2048
	ds_read_b128 v[174:177], v80 offset:4096
	ds_read_b128 v[180:183], v80 offset:6144
	ds_read_b128 v[184:187], v80 offset:8192
	ds_read_b128 v[188:191], v80 offset:10240
	ds_read_b128 v[192:195], v80 offset:12288
	ds_read_b128 v[196:199], v80 offset:14336
	global_load_lds_dwordx4 v[200:201], off
	v_lshl_add_u64 v[200:201], v[142:143], 0, s[38:39]
	s_add_i32 m0, s16, 0xc000
	s_nop 0
	global_load_lds_dwordx4 v[200:201], off
	v_lshl_add_u64 v[200:201], v[136:137], 0, s[38:39]
	s_add_i32 m0, s16, 0x6000
	s_nop 0
	global_load_lds_dwordx4 v[200:201], off
	v_lshl_add_u64 v[200:201], v[144:145], 0, s[38:39]
	s_add_i32 m0, s16, 0xe000
	s_nop 0
	global_load_lds_dwordx4 v[200:201], off
	s_cmp_lg_u32 s101, 0
	s_cbranch_scc1 .Lg1_dtalt2
	s_waitcnt lgkmcnt(0)
	v_mfma_f32_16x16x32_bf16 v[126:129], v[150:153], v[166:169], v[126:129]
	v_mfma_f32_16x16x32_bf16 v[122:125], v[154:157], v[166:169], v[122:125]
	v_mfma_f32_16x16x32_bf16 v[118:121], v[158:161], v[166:169], v[118:121]
	v_mfma_f32_16x16x32_bf16 v[114:117], v[162:165], v[166:169], v[114:117]
	v_mfma_f32_16x16x32_bf16 v[110:113], v[150:153], v[170:173], v[110:113]
	v_mfma_f32_16x16x32_bf16 v[106:109], v[154:157], v[170:173], v[106:109]
	v_mfma_f32_16x16x32_bf16 v[102:105], v[158:161], v[170:173], v[102:105]
	v_mfma_f32_16x16x32_bf16 v[98:101], v[162:165], v[170:173], v[98:101]
	v_mfma_f32_16x16x32_bf16 v[94:97], v[150:153], v[174:177], v[94:97]
	v_mfma_f32_16x16x32_bf16 v[90:93], v[154:157], v[174:177], v[90:93]
	v_mfma_f32_16x16x32_bf16 v[86:89], v[158:161], v[174:177], v[86:89]
	v_mfma_f32_16x16x32_bf16 v[82:85], v[162:165], v[174:177], v[82:85]
	v_mfma_f32_16x16x32_bf16 v[76:79], v[150:153], v[180:183], v[76:79]
	v_mfma_f32_16x16x32_bf16 v[72:75], v[154:157], v[180:183], v[72:75]
	v_mfma_f32_16x16x32_bf16 v[68:71], v[158:161], v[180:183], v[68:71]
	v_mfma_f32_16x16x32_bf16 v[64:67], v[162:165], v[180:183], v[64:67]
	v_mfma_f32_16x16x32_bf16 v[60:63], v[150:153], v[184:187], v[60:63]
	v_mfma_f32_16x16x32_bf16 v[56:59], v[154:157], v[184:187], v[56:59]
	v_mfma_f32_16x16x32_bf16 v[52:55], v[158:161], v[184:187], v[52:55]
	v_mfma_f32_16x16x32_bf16 v[48:51], v[162:165], v[184:187], v[48:51]
	v_mfma_f32_16x16x32_bf16 v[44:47], v[150:153], v[188:191], v[44:47]
	v_mfma_f32_16x16x32_bf16 v[40:43], v[154:157], v[188:191], v[40:43]
	v_mfma_f32_16x16x32_bf16 v[36:39], v[158:161], v[188:191], v[36:39]
	v_mfma_f32_16x16x32_bf16 v[32:35], v[162:165], v[188:191], v[32:35]
	v_mfma_f32_16x16x32_bf16 v[28:31], v[150:153], v[192:195], v[28:31]
	v_mfma_f32_16x16x32_bf16 v[24:27], v[154:157], v[192:195], v[24:27]
	v_mfma_f32_16x16x32_bf16 v[20:23], v[158:161], v[192:195], v[20:23]
	v_mfma_f32_16x16x32_bf16 v[16:19], v[162:165], v[192:195], v[16:19]
	v_mfma_f32_16x16x32_bf16 v[12:15], v[150:153], v[196:199], v[12:15]
	v_mfma_f32_16x16x32_bf16 v[8:11], v[154:157], v[196:199], v[8:11]
	v_mfma_f32_16x16x32_bf16 v[4:7], v[158:161], v[196:199], v[4:7]
	v_mfma_f32_16x16x32_bf16 v[0:3], v[162:165], v[196:199], v[0:3]
; template <bool LOWREG = false>
; __device__ __forceinline__ void gemm_core(const bf16_t* __restrict__ A, int lda, const bf16_t* __restrict__ Bt, int ldb, int K, f32x4 (&acc)[8][4], unsigned char* smem, int tid) {
;     ...
;         for (int ks = 0; ks < 2; ++ks) {
;             bf16x8 bfr[4], af[8];
;             const int co = ((ks * 4 + kq) ^ swz) * 16;
; #pragma unroll
;             for (int ni = 0; ni < 4; ++ni) bfr[ni] = *(const bf16x8*)(sb + boff + ni * 2048 + co);
; #pragma unroll
;             for (int mi = 0; mi < 8; ++mi) af[mi] = *(const bf16x8*)(sb + aoff + mi * 2048 + co);
;             if (more) { G_ISSUE1(kt + 1, st ^ 1, ks * 2); G_ISSUE1(kt + 1, st ^ 1, ks * 2 + 1); }
;             __builtin_amdgcn_sched_barrier(0);
;             __builtin_amdgcn_s_setprio(1);
; #pragma unroll
;             for (int mi = 0; mi < 8; ++mi)
; #pragma unroll
;                 for (int ni = 0; ni < 4; ++ni) acc[mi][ni] = __builtin_amdgcn_mfma_f32_16x16x32_bf16(bfr[ni], af[mi], acc[mi][ni], 0, 0, 0);
;             __builtin_amdgcn_s_setprio(0);
;             __builtin_amdgcn_sched_barrier(0);
;         }
;         } else {
; #pragma unroll
;         for (int ks = 0; ks < 2; ++ks) {
;             bf16x8 bfr[4];
;             const int co = ((ks * 4 + kq) ^ swz) * 16;
; #pragma unroll
;             for (int ni = 0; ni < 4; ++ni) bfr[ni] = *(const bf16x8*)(sb + boff + ni * 2048 + co);
; #pragma unroll
;             for (int mh = 0; mh < 2; ++mh) {
;                 bf16x8 af[4];
; #pragma unroll
;                 for (int mi = 0; mi < 4; ++mi) af[mi] = *(const bf16x8*)(sb + aoff + (mh * 4 + mi) * 2048 + co);
;                 if (more) G_ISSUE1(kt + 1, st ^ 1, ks * 2 + mh);
;                 __builtin_amdgcn_sched_barrier(0);
;                 __builtin_amdgcn_s_setprio(1);
; #pragma unroll
;                 for (int mi = 0; mi < 4; ++mi)
; #pragma unroll
;                     for (int ni = 0; ni < 4; ++ni) acc[mh * 4 + mi][ni] = __builtin_amdgcn_mfma_f32_16x16x32_bf16(bfr[ni], af[mi], acc[mh * 4 + mi][ni], 0, 0, 0);
;                 __builtin_amdgcn_s_setprio(0);
;                 __builtin_amdgcn_sched_barrier(0);
;             }
;         }
;         }
;         asm volatile("s_waitcnt vmcnt(0)" ::: "memory");
;         __syncthreads();
.Lg1_dtskip2:
	s_waitcnt lgkmcnt(0)
	s_add_i32 s12, s12, 0x10000
	s_waitcnt vmcnt(0)
	s_add_u32 s38, s38, 0x80
	s_addc_u32 s39, s39, 0
	s_cmpk_lg_i32 s38, 0x780
	s_waitcnt vmcnt(0)
	s_barrier
	s_cbranch_scc1 .LBB0_255
	s_add_i32 s9, 0, 0x10000
	v_add_u32_e32 v80, s9, v149
	v_add_u32_e32 v149, v80, v148
	ds_read_b128 v[130:133], v149 offset:14336
	ds_read_b128 v[134:137], v149 offset:12288
	ds_read_b128 v[138:141], v149 offset:10240
	ds_read_b128 v[142:145], v149 offset:8192
	ds_read_b128 v[150:153], v149 offset:6144
	ds_read_b128 v[154:157], v149 offset:4096
	ds_read_b128 v[158:161], v149 offset:2048
	ds_read_b128 v[162:165], v149
	v_add_u32_e32 v147, s9, v147
	v_add_u32_e32 v148, v147, v148
	ds_read_b128 v[166:169], v148 offset:38912
	ds_read_b128 v[170:173], v148 offset:36864
	ds_read_b128 v[174:177], v148 offset:34816
	ds_read_b128 v[180:183], v148 offset:32768
	s_cmp_lg_u32 s101, 0
	s_cbranch_scc1 .Lg1_dtalt3
	s_waitcnt lgkmcnt(0)
	v_mfma_f32_16x16x32_bf16 v[126:129], v[180:183], v[162:165], v[126:129]
	v_mfma_f32_16x16x32_bf16 v[122:125], v[174:177], v[162:165], v[122:125]
	v_mfma_f32_16x16x32_bf16 v[118:121], v[170:173], v[162:165], v[118:121]
	v_mfma_f32_16x16x32_bf16 v[114:117], v[166:169], v[162:165], v[114:117]
	v_mfma_f32_16x16x32_bf16 v[110:113], v[180:183], v[158:161], v[110:113]
	v_mfma_f32_16x16x32_bf16 v[106:109], v[174:177], v[158:161], v[106:109]
	v_mfma_f32_16x16x32_bf16 v[102:105], v[170:173], v[158:161], v[102:105]
	v_mfma_f32_16x16x32_bf16 v[98:101], v[166:169], v[158:161], v[98:101]
	v_mfma_f32_16x16x32_bf16 v[94:97], v[180:183], v[154:157], v[94:97]
	v_mfma_f32_16x16x32_bf16 v[90:93], v[174:177], v[154:157], v[90:93]
	v_mfma_f32_16x16x32_bf16 v[86:89], v[170:173], v[154:157], v[86:89]
	v_mfma_f32_16x16x32_bf16 v[82:85], v[166:169], v[154:157], v[82:85]
	v_mfma_f32_16x16x32_bf16 v[76:79], v[180:183], v[150:153], v[76:79]
	v_mfma_f32_16x16x32_bf16 v[72:75], v[174:177], v[150:153], v[72:75]
	v_mfma_f32_16x16x32_bf16 v[68:71], v[170:173], v[150:153], v[68:71]
	v_mfma_f32_16x16x32_bf16 v[64:67], v[166:169], v[150:153], v[64:67]
	v_mfma_f32_16x16x32_bf16 v[60:63], v[180:183], v[142:145], v[60:63]
	v_mfma_f32_16x16x32_bf16 v[56:59], v[174:177], v[142:145], v[56:59]
	v_mfma_f32_16x16x32_bf16 v[52:55], v[170:173], v[142:145], v[52:55]
	v_mfma_f32_16x16x32_bf16 v[48:51], v[166:169], v[142:145], v[48:51]
	v_mfma_f32_16x16x32_bf16 v[44:47], v[180:183], v[138:141], v[44:47]
	v_mfma_f32_16x16x32_bf16 v[40:43], v[174:177], v[138:141], v[40:43]
	v_mfma_f32_16x16x32_bf16 v[36:39], v[170:173], v[138:141], v[36:39]
	v_mfma_f32_16x16x32_bf16 v[32:35], v[166:169], v[138:141], v[32:35]
	v_mfma_f32_16x16x32_bf16 v[28:31], v[180:183], v[134:137], v[28:31]
	v_mfma_f32_16x16x32_bf16 v[24:27], v[174:177], v[134:137], v[24:27]
	v_mfma_f32_16x16x32_bf16 v[20:23], v[170:173], v[134:137], v[20:23]
	v_mfma_f32_16x16x32_bf16 v[16:19], v[166:169], v[134:137], v[16:19]
	v_mfma_f32_16x16x32_bf16 v[12:15], v[180:183], v[130:133], v[12:15]
	v_mfma_f32_16x16x32_bf16 v[8:11], v[174:177], v[130:133], v[8:11]
	v_mfma_f32_16x16x32_bf16 v[4:7], v[170:173], v[130:133], v[4:7]
	v_mfma_f32_16x16x32_bf16 v[0:3], v[166:169], v[130:133], v[0:3]
.Lg1_dtskip3:
	s_waitcnt lgkmcnt(0)
	v_add_u32_e32 v80, v80, v146
	ds_read_b128 v[130:133], v80 offset:14336
	ds_read_b128 v[134:137], v80 offset:12288
	ds_read_b128 v[138:141], v80 offset:10240
	ds_read_b128 v[142:145], v80 offset:8192
	ds_read_b128 v[148:151], v80 offset:6144
	ds_read_b128 v[152:155], v80 offset:4096
	ds_read_b128 v[156:159], v80 offset:2048
	ds_read_b128 v[160:163], v80
	v_add_u32_e32 v80, v147, v146
	ds_read_b128 v[164:167], v80 offset:38912
	ds_read_b128 v[168:171], v80 offset:36864
	ds_read_b128 v[172:175], v80 offset:34816
	ds_read_b128 v[180:183], v80 offset:32768
	s_cmp_lg_u32 s101, 0
	s_cbranch_scc1 .Lg1_dtalt4
	s_waitcnt lgkmcnt(0)
	v_mfma_f32_16x16x32_bf16 v[126:129], v[180:183], v[160:163], v[126:129]
	v_mfma_f32_16x16x32_bf16 v[122:125], v[172:175], v[160:163], v[122:125]
	v_mfma_f32_16x16x32_bf16 v[118:121], v[168:171], v[160:163], v[118:121]
	v_mfma_f32_16x16x32_bf16 v[114:117], v[164:167], v[160:163], v[114:117]
	v_mfma_f32_16x16x32_bf16 v[110:113], v[180:183], v[156:159], v[110:113]
	v_mfma_f32_16x16x32_bf16 v[106:109], v[172:175], v[156:159], v[106:109]
	v_mfma_f32_16x16x32_bf16 v[102:105], v[168:171], v[156:159], v[102:105]
	v_mfma_f32_16x16x32_bf16 v[98:101], v[164:167], v[156:159], v[98:101]
	v_mfma_f32_16x16x32_bf16 v[94:97], v[180:183], v[152:155], v[94:97]
	v_mfma_f32_16x16x32_bf16 v[90:93], v[172:175], v[152:155], v[90:93]
	v_mfma_f32_16x16x32_bf16 v[86:89], v[168:171], v[152:155], v[86:89]
	v_mfma_f32_16x16x32_bf16 v[82:85], v[164:167], v[152:155], v[82:85]
	v_mfma_f32_16x16x32_bf16 v[76:79], v[180:183], v[148:151], v[76:79]
	v_mfma_f32_16x16x32_bf16 v[72:75], v[172:175], v[148:151], v[72:75]
	v_mfma_f32_16x16x32_bf16 v[68:71], v[168:171], v[148:151], v[68:71]
	v_mfma_f32_16x16x32_bf16 v[64:67], v[164:167], v[148:151], v[64:67]
	v_mfma_f32_16x16x32_bf16 v[60:63], v[180:183], v[142:145], v[60:63]
	v_mfma_f32_16x16x32_bf16 v[56:59], v[172:175], v[142:145], v[56:59]
	v_mfma_f32_16x16x32_bf16 v[52:55], v[168:171], v[142:145], v[52:55]
	v_mfma_f32_16x16x32_bf16 v[48:51], v[164:167], v[142:145], v[48:51]
	v_mfma_f32_16x16x32_bf16 v[44:47], v[180:183], v[138:141], v[44:47]
	v_mfma_f32_16x16x32_bf16 v[40:43], v[172:175], v[138:141], v[40:43]
	v_mfma_f32_16x16x32_bf16 v[36:39], v[168:171], v[138:141], v[36:39]
	v_mfma_f32_16x16x32_bf16 v[32:35], v[164:167], v[138:141], v[32:35]
	v_mfma_f32_16x16x32_bf16 v[28:31], v[180:183], v[134:137], v[28:31]
	v_mfma_f32_16x16x32_bf16 v[24:27], v[172:175], v[134:137], v[24:27]
	v_mfma_f32_16x16x32_bf16 v[20:23], v[168:171], v[134:137], v[20:23]
	v_mfma_f32_16x16x32_bf16 v[16:19], v[164:167], v[134:137], v[16:19]
	v_mfma_f32_16x16x32_bf16 v[12:15], v[180:183], v[130:133], v[12:15]
	v_mfma_f32_16x16x32_bf16 v[8:11], v[172:175], v[130:133], v[8:11]
	v_mfma_f32_16x16x32_bf16 v[4:7], v[168:171], v[130:133], v[4:7]
	v_mfma_f32_16x16x32_bf16 v[0:3], v[164:167], v[130:133], v[0:3]
.Lg1_dtskip4:
	s_setprio 0
	s_waitcnt lgkmcnt(0)
	v_mov_b32_e32 v181, v210
	s_waitcnt vmcnt(0)
	s_barrier
	s_cmp_lg_u32 s98, 0
	s_cbranch_scc1 .LBB0_253
	s_nop 0
	v_readfirstlane_b32 s9, v181
	s_ashr_i32 s57, s9, 8
	s_and_b32 s55, s9, 0xc0
	s_lshl_b32 s9, s9, 8
	s_and_b32 s9, s9, 0xffffc000
	v_bfe_u32 v156, v181, 4, 2
	s_or_b32 s54, s55, s36
	s_add_i32 s61, s9, 0
	v_and_b32_e32 v230, 63, v181
	v_and_b32_e32 v231, 15, v181
	v_lshlrev_b32_e32 v157, 2, v156
	s_cmpk_gt_i32 s54, 0x27f
	s_mov_b64 s[36:37], -1
	s_cbranch_scc1 .LBB0_259
	s_andn2_b64 vcc, exec, s[36:37]
	v_and_b32_e32 v179, 7, v181
	s_cbranch_vccz .LBB0_521
